# P3 work-queue pop: compute-first WGs request next ticket one item ahead (held in v220, restored at loop exit)
# baseline (speedup 1.0000x reference)
; DEV int lane_id() { int l; asm volatile("v_mbcnt_lo_u32_b32 %0, -1, 0\n\tv_mbcnt_hi_u32_b32 %0, -1, %0" : "=v"(l)); return l; }
; #define LAS __attribute__((address_space(3)))
; __global__ void __launch_bounds__(512, 2) mk_fwd(MKArgs args) {
;     ...
;             { volatile LAS unsigned* LQ = (volatile LAS unsigned*)(ldsl + LDSCTL_OFF + 512);
;               unsigned* qd = (unsigned*)(ws + WS_CTL) + CW_Q3 + 128 * l; unsigned* qa = qd + 64;
;               const bool dclass = (bx >> 3) == 19 || (bx >> 3) == 27;
;               constexpr unsigned ND = SB * NSPLIT, NA = NB * MH * 8 + M / 256;
;               for (;;) {
;                   if (wave_s == 0 && lane_id() == 0) { unsigned kind = 2u, idx = 0u;
;                       if (dclass) { idx = __hip_atomic_fetch_add(qd, 1u, __ATOMIC_RELAXED, __HIP_MEMORY_SCOPE_AGENT); if (idx < ND) kind = 0u; else { idx = __hip_atomic_fetch_add(qa, 1u, __ATOMIC_RELAXED, __HIP_MEMORY_SCOPE_AGENT); if (idx < NA) kind = 1u; } }
;                       else { idx = __hip_atomic_fetch_add(qa, 1u, __ATOMIC_RELAXED, __HIP_MEMORY_SCOPE_AGENT); if (idx < NA) kind = 1u; else { idx = __hip_atomic_fetch_add(qd, 1u, __ATOMIC_RELAXED, __HIP_MEMORY_SCOPE_AGENT); if (idx < ND) kind = 0u; } }
;                       LQ[0] = kind; LQ[1] = idx; }
;                   __syncthreads();
;                   const unsigned kind = LQ[0], idx = LQ[1];
;                   __syncthreads();
.LBB0_1240:
	s_waitcnt lgkmcnt(0)
	v_readlane_b32 s10, v255, 0
	v_readlane_b32 s14, v254, 1
	s_lshl_b32 s4, s10, 11
	v_readlane_b32 s15, v254, 2
	v_readlane_b32 s11, v255, 1
	s_barrier
	v_writelane_b32 v255, s4, 31
	v_readlane_b32 s4, v254, 9
	s_lshl_b32 s6, s10, 12
	s_load_dwordx2 s[22:23], s[14:15], 0x120
	v_readlane_b32 s5, v254, 10
	v_writelane_b32 v255, s6, 33
	s_load_dword s4, s[4:5], 0x0
	v_readlane_b32 s5, v254, 0
	v_writelane_b32 v255, s7, 34
	s_mov_b32 s6, s57
	s_waitcnt lgkmcnt(0)
	s_lshl_b64 s[0:1], s[10:11], 14
	s_lshl_b64 s[2:3], s[10:11], 20
	s_add_i32 s50, s6, 0
	v_readlane_b32 s4, v254, 52
	s_add_u32 s4, s22, s4
	s_addc_u32 s6, s23, 0
	s_add_i32 s51, s50, 0x20200
	s_lshl_b64 s[8:9], s[38:39], 2
	s_add_u32 s7, s22, s8
	v_writelane_b32 v255, s8, 40
	s_mul_hi_u32 s26, s10, 0x1400
	s_mul_i32 s27, s10, 0x1400
	v_writelane_b32 v255, s9, 41
	s_addc_u32 s8, s23, s9
	s_add_u32 s12, s7, 0xa6040
	s_addc_u32 s13, s8, 0
	v_writelane_b32 v255, s12, 26
	s_nop 1
	v_writelane_b32 v255, s13, 27
	s_add_u32 s12, s7, 0xa6140
	s_addc_u32 s13, s8, 0
	s_and_b32 s5, s5, 0xffffffb8
	s_cmpk_lg_i32 s5, 0x98
	s_cselect_b64 s[8:9], -1, 0
	s_add_i32 s52, s50, 0x20204
	s_add_i32 s53, s50, 0x17a00
	s_add_i32 s62, s50, 0x19e00
	s_add_u32 s63, s22, 0x1a798300
	s_addc_u32 s72, s23, 0
	s_add_i32 s73, s50, 0x15000
	s_add_i32 s78, s50, 0x1a000
	s_add_i32 s5, s50, 0x18e00
	s_add_u32 s2, s22, s2
	s_addc_u32 s3, s23, s3
	s_add_u32 s88, s2, 0x1a7d5300
	s_addc_u32 s89, s3, 0
	s_add_u32 s0, s22, s0
	s_addc_u32 s1, s23, s1
	s_add_u32 s40, s0, 0x1abd5300
	s_addc_u32 s41, s1, 0
	v_writelane_b32 v254, s5, 50
	s_add_u32 s0, s22, 0x9c400
	v_writelane_b32 v254, s0, 62
	s_addc_u32 s0, s23, 0
	v_writelane_b32 v254, s0, 60
	s_add_u32 s0, s22, 0x1a7c0300
	s_addc_u32 s37, s23, 0
	v_writelane_b32 v254, s0, 54
	s_add_u32 s0, s22, 0x1a7c5500
	v_writelane_b32 v254, s0, 58
	v_writelane_b32 v255, s12, 29
	v_readlane_b32 s0, v254, 47
	v_readlane_b32 s1, v254, 48
	v_writelane_b32 v255, s13, 30
	v_writelane_b32 v255, s8, 6
	s_addc_u32 s36, s23, 0
	s_lshl_b64 s[2:3], s[0:1], 2
	v_writelane_b32 v255, s9, 7
	s_add_u32 s0, s22, s2
	v_writelane_b32 v255, s2, 42
	s_addc_u32 s1, s23, s3
	s_add_u32 s0, s0, 0xce800
	v_writelane_b32 v255, s3, 43
	s_addc_u32 s1, s1, 0
	v_writelane_b32 v255, s0, 44
	s_nop 1
	v_writelane_b32 v255, s1, 45
	s_add_u32 s0, s22, 0xee58100
	v_writelane_b32 v255, s0, 10
	s_addc_u32 s0, s23, 0
	v_writelane_b32 v255, s0, 12
	s_add_u32 s0, s22, 0xfe58100
	v_writelane_b32 v254, s0, 49
	s_addc_u32 s0, s23, 0
	v_writelane_b32 v255, s0, 8
	s_add_u32 s0, s22, 0x10658100
	v_writelane_b32 v255, s0, 32
	s_addc_u32 s0, s23, 0
	v_writelane_b32 v255, s0, 18
	s_add_u32 s0, s22, 0x11658100
	v_writelane_b32 v255, s0, 20
	s_addc_u32 s0, s23, 0
	v_writelane_b32 v255, s0, 22
	s_add_u32 s0, s22, 0x11758100
	v_writelane_b32 v255, s0, 24
	s_addc_u32 s0, s23, 0
	v_writelane_b32 v255, s0, 28
	s_add_u32 s0, s22, 0xbc800
	v_writelane_b32 v255, s0, 14
	s_addc_u32 s0, s23, 0
	s_add_u32 s60, s22, 0x12758100
	s_addc_u32 s61, s23, 0
	s_add_u32 s64, s4, 0x4e0000
	s_addc_u32 s65, s6, 0
	s_add_u32 s42, s22, 0x12f58100
	s_addc_u32 s43, s23, 0
	s_add_i32 s38, s50, 0x10000
	v_writelane_b32 v255, s0, 46
	s_add_u32 s0, s4, 0x4f0000
	s_addc_u32 s1, s6, 0
	s_add_i32 s39, s50, 0x14000
	s_add_u32 s20, s4, 0x4e0080
	s_addc_u32 s21, s6, 0
	s_add_i32 s24, s50, 0x18000
	s_add_u32 s70, s4, 0x4f0080
	s_addc_u32 s71, s6, 0
	s_add_i32 s25, s50, 0x1c000
	s_add_u32 s80, s4, 0x4e0100
	s_addc_u32 s81, s6, 0
	s_add_u32 s2, s4, 0x4f0100
	s_addc_u32 s3, s6, 0
	s_add_u32 s58, s4, 0x4e0180
	s_addc_u32 s59, s6, 0
	s_add_u32 s54, s4, 0x4f0180
	s_addc_u32 s55, s6, 0
	v_readlane_b32 s4, v254, 40
	v_readlane_b32 s5, v254, 41
	s_and_b64 vcc, exec, s[4:5]
	s_cbranch_vccnz .Lq3_nopre
	v_mbcnt_lo_u32_b32 v0, -1, 0
	v_mbcnt_hi_u32_b32 v0, -1, v0
	s_nop 0
	v_cmp_eq_u32_e32 vcc, 0, v0
	s_and_saveexec_b64 s[4:5], vcc
	v_readlane_b32 s6, v255, 6
	v_readlane_b32 s8, v255, 29
	v_readlane_b32 s9, v255, 30
	v_readlane_b32 s10, v255, 26
	v_readlane_b32 s11, v255, 27
	s_cmp_lg_u32 s6, 0
	s_cselect_b32 s12, s8, s10
	s_cselect_b32 s13, s9, s11
	s_cselect_b32 s8, s10, s8
	s_cselect_b32 s9, s11, s9
	s_movk_i32 vcc_lo, 0x240
	s_movk_i32 vcc_hi, 0x100
	s_cselect_b32 s16, vcc_lo, vcc_hi
	s_cselect_b32 s17, vcc_hi, vcc_lo
	s_cselect_b32 s6, 1, 0
	v_mov_b32_e32 v2, 1
	s_cmp_lg_u32 s6, 0
	s_cbranch_scc0 .Lq3_nopre2
	global_atomic_add v220, v1, v2, s[12:13] sc0
.Lq3_nopre2:
	s_or_b64 exec, exec, s[4:5]
.Lq3_nopre:
	s_branch .LBB0_1246
.LBB0_1241:
	s_or_b64 exec, exec, s[10:11]

; DEV int lane_id() { int l; asm volatile("v_mbcnt_lo_u32_b32 %0, -1, 0\n\tv_mbcnt_hi_u32_b32 %0, -1, %0" : "=v"(l)); return l; }
; __global__ void __launch_bounds__(512, 2) mk_fwd(MKArgs args) {
;     ...
;               for (;;) {
;                   if (wave_s == 0 && lane_id() == 0) { unsigned kind = 2u, idx = 0u;
;                       if (dclass) { idx = __hip_atomic_fetch_add(qd, 1u, __ATOMIC_RELAXED, __HIP_MEMORY_SCOPE_AGENT); if (idx < ND) kind = 0u; else { idx = __hip_atomic_fetch_add(qa, 1u, __ATOMIC_RELAXED, __HIP_MEMORY_SCOPE_AGENT); if (idx < NA) kind = 1u; } }
;                       else { idx = __hip_atomic_fetch_add(qa, 1u, __ATOMIC_RELAXED, __HIP_MEMORY_SCOPE_AGENT); if (idx < NA) kind = 1u; else { idx = __hip_atomic_fetch_add(qd, 1u, __ATOMIC_RELAXED, __HIP_MEMORY_SCOPE_AGENT); if (idx < ND) kind = 0u; } }
;                       LQ[0] = kind; LQ[1] = idx; }
;                   __syncthreads();
;                   const unsigned kind = LQ[0], idx = LQ[1];
;                   __syncthreads();
.LBB0_1246:
	v_readlane_b32 s4, v254, 40
	v_readlane_b32 s5, v254, 41
	s_and_b64 vcc, exec, s[4:5]
	s_cbranch_vccnz .LBB0_1262
	v_mbcnt_lo_u32_b32 v0, -1, 0
	v_mbcnt_hi_u32_b32 v0, -1, v0
	s_nop 0
	v_cmp_eq_u32_e32 vcc, 0, v0
	s_and_saveexec_b64 s[4:5], vcc
	v_readlane_b32 s6, v255, 6
	v_readlane_b32 s8, v255, 29
	v_readlane_b32 s9, v255, 30
	v_readlane_b32 s10, v255, 26
	v_readlane_b32 s11, v255, 27
	s_cmp_lg_u32 s6, 0
	s_cselect_b32 s12, s8, s10
	s_cselect_b32 s13, s9, s11
	s_cselect_b32 s8, s10, s8
	s_cselect_b32 s9, s11, s9
	s_movk_i32 vcc_lo, 0x240
	s_movk_i32 vcc_hi, 0x100
	s_cselect_b32 s16, vcc_lo, vcc_hi
	s_cselect_b32 s17, vcc_hi, vcc_lo
	s_cselect_b32 s6, 1, 0
	v_mov_b32_e32 v2, 1
	s_cmp_lg_u32 s6, 0
	s_cbranch_scc1 .Lq3_pref
	global_atomic_add v220, v1, v2, s[12:13] sc0
	s_waitcnt vmcnt(0)
	v_readfirstlane_b32 s7, v220
	s_nop 1
	s_branch .Lq3_got
.Lq3_pref:
	s_waitcnt vmcnt(0)
	v_readfirstlane_b32 s7, v220
	s_nop 0
	global_atomic_add v220, v1, v2, s[12:13] sc0
.Lq3_got:
	v_mov_b32_e32 v0, s7
	v_mov_b32_e32 v3, s6
	s_cmp_lt_u32 s7, s16
	s_cbranch_scc1 .Lq3_have
	global_atomic_add v0, v1, v2, s[8:9] sc0
	s_xor_b32 s6, s6, 1
	s_waitcnt vmcnt(0)
	v_readfirstlane_b32 s7, v0
	s_cmp_lt_u32 s7, s17
	s_cselect_b32 s6, s6, 2
	v_mov_b32_e32 v3, s6
.Lq3_have:
	v_mov_b32_e32 v2, s51
	ds_write_b32 v2, v3
	v_mov_b32_e32 v2, s52
	ds_write_b32 v2, v0
	s_or_b64 exec, exec, s[4:5]

; DEV void wg_wait(const unsigned* c0, unsigned n0, const unsigned* c1, unsigned n1, int wave_s) { if (wave_s == 0) { pg8::poll_ge(c0, n0); if (c1) pg8::poll_ge(c1, n1); pg8::acq_agent(); } __syncthreads(); }
; #define SEAM(k) do { if (IN(k) && IN((k) + 1)) xcd_barrier(bar, wave_s == 0 && lane_id() == 0); } while (0)
; __global__ void __launch_bounds__(512, 2) mk_fwd(MKArgs args) {
;     ...
;         if ((int)gridDim.x != 256) SEAM(pb + 2);
;         if (IN(pb + 3)) { LAYER_PTRS
;             const bool mrg = G == 256; unsigned* ctl = (unsigned*)(ws + WS_CTL);
;             const int pm4 = 8 * (bx & 7) + 7 - (bx >> 5), pn4 = (bx >> 3) & 3;
;             if (mrg) wg_wait(ctl + CW_MX + (l * 64 + pm4) * 64, 9u * 8u, ctl + CW_GL + (l * NB + (bx & 7)) * 64, (unsigned)GH, wave_s);
.LBB0_1424:
	s_waitcnt vmcnt(0)
	v_mov_b32_e32 v220, 0x3fb8aa3b
	v_readlane_b32 s0, v254, 9
	v_readlane_b32 s1, v254, 10
	s_load_dword s0, s[0:1], 0x0
	s_waitcnt lgkmcnt(0)
	s_cmpk_lg_i32 s0, 0x100
	v_writelane_b32 v255, s0, 44
	s_cselect_b64 s[0:1], -1, 0
	v_writelane_b32 v255, s0, 47
	s_and_b64 vcc, exec, s[0:1]
	s_nop 0
	v_writelane_b32 v255, s1, 48
	s_nop 0
	v_readlane_b32 s22, v255, 0
	v_readlane_b32 s23, v255, 1
	s_cbranch_vccz .LBB0_1480
	v_readlane_b32 s0, v254, 40
	v_readlane_b32 s1, v254, 41
	s_and_b64 vcc, exec, s[0:1]
	s_mov_b64 s[2:3], 0
	s_cbranch_vccnz .LBB0_1427
	v_mbcnt_lo_u32_b32 v0, -1, 0
	v_mbcnt_hi_u32_b32 v0, -1, v0
	s_nop 0
	v_cmp_eq_u32_e32 vcc, 0, v0
	s_and_b64 s[2:3], vcc, exec
